# FFN2-up last partial round split into 128-row half units on 224 workgroups (K-loop copies without the other A half's DMA/reads/MFMAs, vmcnt(6)); W2D conversion moved to workgroups >=224 and split betw
# speedup vs baseline: 1.0154x; 1.0073x over previous
.Ld1b_268:
	s_cmpk_gt_i32 s61, 0xdbf
	s_cbranch_scc1 .Ld1b_end
	s_cmpk_lt_i32 s61, 0x840
	s_cbranch_scc1 .Ld1b_267
	s_cmpk_gt_i32 s61, 0xaff
	s_mov_b64 s[0:1], -1
	s_cbranch_scc0 .Ld1b_314
	s_lshl_b32 s0, s21, 2
	s_and_b32 s10, s0, 0xf80
	s_cmpk_gt_u32 s61, 0x107f
	s_mov_b64 s[0:1], -1
	s_cbranch_scc0 .Ld1b_309
	s_cmpk_gt_u32 s61, 0x167f
	s_cbranch_scc0 .Ld1b_280
	s_cmpk_gt_u32 s61, 0x187f
	s_cbranch_scc0 .Ld1b_275
	s_lshr_b32 s8, s21, 5
	s_lshr_b32 s4, s20, 7
	s_lshl_b64 s[0:1], s[4:5], 20
	s_and_b32 s4, s8, 15
	s_lshl_b32 s4, s4, 7
	s_or_b32 s0, s0, s4
	s_and_b32 s4, s23, 0x1c0
	v_or_b32_e32 v2, s4, v58
	v_lshl_or_b32 v42, v2, 11, s0
	v_mov_b32_e32 v43, s1
	v_or_b32_e32 v2, s4, v59
	v_lshl_add_u64 v[28:29], v[12:13], 0, v[42:43]
	v_lshl_or_b32 v42, v2, 11, s0
	v_or_b32_e32 v2, s4, v60
	v_lshl_add_u64 v[30:31], v[12:13], 0, v[42:43]
	v_lshl_or_b32 v42, v2, 11, s0
	v_or_b32_e32 v2, s4, v61
	v_lshl_add_u64 v[32:33], v[12:13], 0, v[42:43]
	v_lshl_or_b32 v42, v2, 11, s0
	v_or_b32_e32 v2, s4, v62
	v_lshl_add_u64 v[34:35], v[12:13], 0, v[42:43]
	v_lshl_or_b32 v42, v2, 11, s0
	v_or_b32_e32 v2, s4, v63
	v_lshl_add_u64 v[36:37], v[12:13], 0, v[42:43]
	v_lshl_or_b32 v42, v2, 11, s0
	v_or_b32_e32 v2, s4, v64
	v_lshl_add_u64 v[38:39], v[12:13], 0, v[42:43]
	v_lshl_or_b32 v42, v2, 11, s0
	v_or_b32_e32 v2, s4, v1
	v_lshl_add_u64 v[40:41], v[12:13], 0, v[42:43]
	v_lshl_or_b32 v42, v2, 11, s0
	v_lshl_add_u64 v[42:43], v[12:13], 0, v[42:43]
	s_mov_b64 s[0:1], 0
	v_mov_b32_e32 v2, v57

.LBB0_974:
	s_add_i32 s52, s52, 1
	s_mul_i32 s0, s52, s53
	s_mul_hi_u32 s1, s52, s3
	s_add_i32 s1, s1, s0
	s_mul_i32 s0, s52, s3
	s_add_u32 s18, s0, s2
	s_addc_u32 s19, s1, s47
	s_mov_b32 s101, 0
	s_cmpk_lg_i32 s3, 0x100
	s_cbranch_scc1 .Lt9_b
	s_cmp_eq_u32 s52, 4
	s_cbranch_scc0 .Lt9_a
	s_cmpk_lt_i32 s2, 0x70
	s_cselect_b32 s101, 1, 2
.Lt9_a:
	s_cmp_eq_u32 s52, 3
	s_cbranch_scc0 .Lt9_b
	s_cmpk_lt_i32 s2, 0x70
	s_cbranch_scc1 .Lt9_b
	s_cmpk_gt_i32 s2, 0xdf
	s_cbranch_scc1 .Lt9_b
	s_sub_u32 s18, s18, 0x70
.Lt9_b:
	v_cmp_gt_i64_e32 vcc, s[18:19], v[140:141]
	v_cmp_lt_i64_e64 s[0:1], s[18:19], v[138:139]
	s_cbranch_vccnz .LBB0_976
	s_ashr_i32 s12, s18, 31
	s_lshr_b32 s12, s12, 29
	s_add_i32 s12, s18, s12
	s_ashr_i32 s13, s12, 3
	s_and_b32 s12, s12, -8
	s_sub_i32 s12, s18, s12
	s_cmp_lt_i32 s12, 0
	s_cselect_b32 s14, s48, 0x6e
	s_mul_i32 s12, s12, s14
	s_add_i32 s12, s12, s13
	s_mul_hi_i32 s13, s12, 0x2e8ba2e9
	s_lshr_b32 s14, s13, 31
	s_ashr_i32 s13, s13, 5
	s_add_i32 s13, s13, s14
	s_lshl_b32 s14, s13, 3
	s_sub_i32 s15, 40, s14
	s_min_i32 s15, s15, 8
	s_abs_i32 s18, s15
	v_cvt_f32_u32_e32 v2, s18
	s_sub_i32 s20, 0, s18
	s_mulk_i32 s13, 0xb0
	s_sub_i32 s13, s12, s13
	v_rcp_iflag_f32_e32 v2, v2
	s_abs_i32 s12, s13
	s_xor_b32 s19, s13, s15
	s_ashr_i32 s19, s19, 31
	v_mul_f32_e32 v2, 0x4f7ffffe, v2
	v_cvt_u32_f32_e32 v2, v2
	s_nop 0
	v_readfirstlane_b32 s21, v2
	s_mul_i32 s20, s20, s21
	s_mul_hi_u32 s20, s21, s20
	s_add_i32 s21, s21, s20
	s_mul_hi_u32 s20, s12, s21
	s_mul_i32 s21, s20, s18
	s_sub_i32 s12, s12, s21
	s_add_i32 s44, s20, 1
	s_sub_i32 s21, s12, s18
	s_cmp_ge_u32 s12, s18
	s_cselect_b32 s20, s44, s20
	s_cselect_b32 s12, s21, s12
	s_add_i32 s21, s20, 1
	s_cmp_ge_u32 s12, s18
	s_cselect_b32 s12, s21, s20
	s_xor_b32 s12, s12, s19
	s_sub_i32 s12, s12, s19
	s_mul_i32 s15, s12, s15
	s_sub_i32 s13, s13, s15
	s_add_i32 s14, s14, s13
.LBB0_976:
	s_ashr_i32 s15, s14, 31
	s_lshl_b64 s[18:19], s[14:15], 19
	s_add_u32 s18, s89, s18
	s_addc_u32 s19, s90, s19
	s_and_b64 s[20:21], s[0:1], exec
	s_cselect_b32 s15, s19, s25
	s_cselect_b32 s60, s18, s24
	s_ashr_i32 s13, s12, 31
	s_lshl_b64 s[20:21], s[12:13], 19
	s_add_u32 s20, s26, s20
	s_addc_u32 s21, s27, s21
	s_and_b64 s[44:45], s[0:1], exec
	s_cselect_b32 s13, s21, s37
	s_cselect_b32 s61, s20, s36
	s_add_u32 s24, s24, 0x40080
	s_addc_u32 s25, s25, 0
	s_add_u32 s62, s36, 0x100
	v_mov_b32_e32 v2, 0
	s_addc_u32 s63, s37, 0
	s_mov_b32 s64, -2
	v_mov_b32_e32 v3, v2
	v_mov_b32_e32 v4, v2
	v_mov_b32_e32 v5, v2
	v_mov_b32_e32 v10, v2
	v_mov_b32_e32 v11, v2
	v_mov_b32_e32 v12, v2
	v_mov_b32_e32 v13, v2
	v_mov_b32_e32 v18, v2
	v_mov_b32_e32 v19, v2
	v_mov_b32_e32 v20, v2
	v_mov_b32_e32 v21, v2
	v_mov_b32_e32 v26, v2
	v_mov_b32_e32 v27, v2
	v_mov_b32_e32 v28, v2
	v_mov_b32_e32 v29, v2
	v_mov_b32_e32 v34, v2
	v_mov_b32_e32 v35, v2
	v_mov_b32_e32 v36, v2
	v_mov_b32_e32 v37, v2
	v_mov_b32_e32 v42, v2
	v_mov_b32_e32 v43, v2
	v_mov_b32_e32 v44, v2
	v_mov_b32_e32 v45, v2
	v_mov_b32_e32 v50, v2
	v_mov_b32_e32 v51, v2
	v_mov_b32_e32 v52, v2
	v_mov_b32_e32 v53, v2
	v_mov_b32_e32 v58, v2
	v_mov_b32_e32 v59, v2
	v_mov_b32_e32 v60, v2
	v_mov_b32_e32 v61, v2
	v_mov_b32_e32 v6, v2
	v_mov_b32_e32 v7, v2
	v_mov_b32_e32 v8, v2
	v_mov_b32_e32 v9, v2
	v_mov_b32_e32 v14, v2
	v_mov_b32_e32 v15, v2
	v_mov_b32_e32 v16, v2
	v_mov_b32_e32 v17, v2
	v_mov_b32_e32 v22, v2
	v_mov_b32_e32 v23, v2
	v_mov_b32_e32 v24, v2
	v_mov_b32_e32 v25, v2
	v_mov_b32_e32 v30, v2
	v_mov_b32_e32 v31, v2
	v_mov_b32_e32 v32, v2
	v_mov_b32_e32 v33, v2
	v_mov_b32_e32 v38, v2
	v_mov_b32_e32 v39, v2
	v_mov_b32_e32 v40, v2
	v_mov_b32_e32 v41, v2
	v_mov_b32_e32 v46, v2
	v_mov_b32_e32 v47, v2
	v_mov_b32_e32 v48, v2
	v_mov_b32_e32 v49, v2
	v_mov_b32_e32 v54, v2
	v_mov_b32_e32 v55, v2
	v_mov_b32_e32 v56, v2
	v_mov_b32_e32 v57, v2
	v_mov_b32_e32 v62, v2
	v_mov_b32_e32 v63, v2
	v_mov_b32_e32 v64, v2
	v_mov_b32_e32 v65, v2
	v_mov_b32_e32 v66, v2
	v_mov_b32_e32 v67, v2
	v_mov_b32_e32 v68, v2
	v_mov_b32_e32 v69, v2
	v_mov_b32_e32 v74, v2
	v_mov_b32_e32 v75, v2
	v_mov_b32_e32 v76, v2
	v_mov_b32_e32 v77, v2
	v_mov_b32_e32 v82, v2
	v_mov_b32_e32 v83, v2
	v_mov_b32_e32 v84, v2
	v_mov_b32_e32 v85, v2
	v_mov_b32_e32 v90, v2
	v_mov_b32_e32 v91, v2
	v_mov_b32_e32 v92, v2
	v_mov_b32_e32 v93, v2
	v_mov_b32_e32 v98, v2
	v_mov_b32_e32 v99, v2
	v_mov_b32_e32 v100, v2
	v_mov_b32_e32 v101, v2
	v_mov_b32_e32 v106, v2
	v_mov_b32_e32 v107, v2
	v_mov_b32_e32 v108, v2
	v_mov_b32_e32 v109, v2
	v_mov_b32_e32 v114, v2
	v_mov_b32_e32 v115, v2
	v_mov_b32_e32 v116, v2
	v_mov_b32_e32 v117, v2
	v_mov_b32_e32 v122, v2
	v_mov_b32_e32 v123, v2
	v_mov_b32_e32 v124, v2
	v_mov_b32_e32 v125, v2
	v_mov_b32_e32 v70, v2
	v_mov_b32_e32 v71, v2
	v_mov_b32_e32 v72, v2
	v_mov_b32_e32 v73, v2
	v_mov_b32_e32 v78, v2
	v_mov_b32_e32 v79, v2
	v_mov_b32_e32 v80, v2
	v_mov_b32_e32 v81, v2
	v_mov_b32_e32 v86, v2
	v_mov_b32_e32 v87, v2
	v_mov_b32_e32 v88, v2
	v_mov_b32_e32 v89, v2
	v_mov_b32_e32 v94, v2
	v_mov_b32_e32 v95, v2
	v_mov_b32_e32 v96, v2
	v_mov_b32_e32 v97, v2
	v_mov_b32_e32 v102, v2
	v_mov_b32_e32 v103, v2
	v_mov_b32_e32 v104, v2
	v_mov_b32_e32 v105, v2
	v_mov_b32_e32 v110, v2
	v_mov_b32_e32 v111, v2
	v_mov_b32_e32 v112, v2
	v_mov_b32_e32 v113, v2
	v_mov_b32_e32 v118, v2
	v_mov_b32_e32 v119, v2
	v_mov_b32_e32 v120, v2
	v_mov_b32_e32 v121, v2
	v_mov_b32_e32 v126, v2
	v_mov_b32_e32 v127, v2
	v_mov_b32_e32 v128, v2
	v_mov_b32_e32 v129, v2
	s_cmp_eq_u32 s101, 1
	s_cbranch_scc1 .Lt9_h0
	s_cmp_eq_u32 s101, 2
	s_cbranch_scc1 .Lt9_h1
.LBB0_977:
	ds_read_b128 v[148:151], v144
	ds_read_b128 v[152:155], v144 offset:1024
	ds_read_b128 v[156:159], v144 offset:2048
	ds_read_b128 v[160:163], v144 offset:3072
	ds_read_b128 v[166:169], v145
	ds_read_b128 v[170:173], v145 offset:1024
	ds_read_b128 v[174:177], v145 offset:2048
	ds_read_b128 v[178:181], v145 offset:3072
	s_add_u32 s36, s24, 0xfffc0080
	s_addc_u32 s37, s25, -1
	s_cmp_eq_u32 s64, 12
	s_cselect_b32 s45, s15, s37
	s_cselect_b32 s44, s60, s36
	s_cselect_b32 s37, s13, s63
	s_cselect_b32 s36, s61, s62
	v_lshl_add_u64 v[214:215], s[24:25], 0, v[134:135]
	s_add_i32 m0, s23, 0xc000
	ds_read_b128 v[182:185], v146
	ds_read_b128 v[186:189], v146 offset:1024
	ds_read_b128 v[190:193], v146 offset:2048
	ds_read_b128 v[194:197], v146 offset:3072
	ds_read_b128 v[198:201], v146 offset:4096
	ds_read_b128 v[202:205], v146 offset:5120
	ds_read_b128 v[206:209], v146 offset:6144
	ds_read_b128 v[210:213], v146 offset:7168
	global_load_lds_dwordx4 v[214:215], off
	v_lshl_add_u64 v[214:215], s[24:25], 0, v[136:137]
	s_add_i32 m0, s23, 0xe000
	s_nop 0
	global_load_lds_dwordx4 v[214:215], off
	s_waitcnt vmcnt(8)
	s_waitcnt lgkmcnt(0)
	s_barrier
	s_setprio 1
	s_waitcnt lgkmcnt(0)
	v_mfma_f32_16x16x32_bf16 v[126:129], v[148:151], v[182:185], v[126:129]
	v_mfma_f32_16x16x32_bf16 v[118:121], v[156:159], v[182:185], v[118:121]
	v_mfma_f32_16x16x32_bf16 v[110:113], v[148:151], v[190:193], v[110:113]
	v_mfma_f32_16x16x32_bf16 v[102:105], v[156:159], v[190:193], v[102:105]
	v_mfma_f32_16x16x32_bf16 v[94:97], v[148:151], v[198:201], v[94:97]
	v_mfma_f32_16x16x32_bf16 v[86:89], v[156:159], v[198:201], v[86:89]
	v_mfma_f32_16x16x32_bf16 v[78:81], v[148:151], v[206:209], v[78:81]
	v_mfma_f32_16x16x32_bf16 v[70:73], v[156:159], v[206:209], v[70:73]
	v_mfma_f32_16x16x32_bf16 v[126:129], v[152:155], v[186:189], v[126:129]
	v_mfma_f32_16x16x32_bf16 v[118:121], v[160:163], v[186:189], v[118:121]
	v_mfma_f32_16x16x32_bf16 v[110:113], v[152:155], v[194:197], v[110:113]
	v_mfma_f32_16x16x32_bf16 v[102:105], v[160:163], v[194:197], v[102:105]
	v_mfma_f32_16x16x32_bf16 v[94:97], v[152:155], v[202:205], v[94:97]
	v_mfma_f32_16x16x32_bf16 v[86:89], v[160:163], v[202:205], v[86:89]
	v_mfma_f32_16x16x32_bf16 v[78:81], v[152:155], v[210:213], v[78:81]
	v_mfma_f32_16x16x32_bf16 v[70:73], v[160:163], v[210:213], v[70:73]
	s_setprio 0
	s_setprio 1
	v_mfma_f32_16x16x32_bf16 v[122:125], v[166:169], v[182:185], v[122:125]
	v_mfma_f32_16x16x32_bf16 v[114:117], v[174:177], v[182:185], v[114:117]
	v_mfma_f32_16x16x32_bf16 v[106:109], v[166:169], v[190:193], v[106:109]
	v_mfma_f32_16x16x32_bf16 v[98:101], v[174:177], v[190:193], v[98:101]
	v_mfma_f32_16x16x32_bf16 v[90:93], v[166:169], v[198:201], v[90:93]
	v_mfma_f32_16x16x32_bf16 v[82:85], v[174:177], v[198:201], v[82:85]
	v_mfma_f32_16x16x32_bf16 v[74:77], v[166:169], v[206:209], v[74:77]
	v_mfma_f32_16x16x32_bf16 v[66:69], v[174:177], v[206:209], v[66:69]
	v_mfma_f32_16x16x32_bf16 v[122:125], v[170:173], v[186:189], v[122:125]
	v_mfma_f32_16x16x32_bf16 v[114:117], v[178:181], v[186:189], v[114:117]
	v_mfma_f32_16x16x32_bf16 v[106:109], v[170:173], v[194:197], v[106:109]
	v_mfma_f32_16x16x32_bf16 v[98:101], v[178:181], v[194:197], v[98:101]
	v_mfma_f32_16x16x32_bf16 v[90:93], v[170:173], v[202:205], v[90:93]
	v_mfma_f32_16x16x32_bf16 v[82:85], v[178:181], v[202:205], v[82:85]
	v_mfma_f32_16x16x32_bf16 v[74:77], v[170:173], v[210:213], v[74:77]
	v_mfma_f32_16x16x32_bf16 v[66:69], v[178:181], v[210:213], v[66:69]
	s_setprio 0
	s_barrier
	s_add_i32 s65, s56, s46
	v_lshl_add_u64 v[214:215], s[36:37], 0, v[130:131]
	s_mov_b32 m0, s65
	ds_read_b128 v[182:185], v146 offset:16384
	ds_read_b128 v[186:189], v146 offset:17408
	ds_read_b128 v[190:193], v146 offset:18432
	ds_read_b128 v[194:197], v146 offset:19456
	ds_read_b128 v[198:201], v146 offset:20480
	ds_read_b128 v[202:205], v146 offset:21504
	ds_read_b128 v[206:209], v146 offset:22528
	ds_read_b128 v[210:213], v146 offset:23552
	global_load_lds_dwordx4 v[214:215], off
	s_add_i32 m0, s65, 0x2000
	s_add_u32 s66, s36, 0x40000
	v_lshl_add_u64 v[216:217], s[36:37], 0, v[132:133]
	s_addc_u32 s67, s37, 0
	s_add_i32 s65, s57, s46
	global_load_lds_dwordx4 v[216:217], off
	v_lshl_add_u64 v[218:219], s[66:67], 0, v[130:131]
	s_mov_b32 m0, s65
	v_lshl_add_u64 v[220:221], s[44:45], 0, v[132:133]
	global_load_lds_dwordx4 v[218:219], off
	v_lshl_add_u64 v[218:219], s[66:67], 0, v[132:133]
	s_add_i32 m0, s65, 0x2000
	s_nop 0
	global_load_lds_dwordx4 v[218:219], off
	v_lshl_add_u64 v[218:219], s[44:45], 0, v[130:131]
	s_mov_b32 m0, s23
	s_nop 0
	global_load_lds_dwordx4 v[218:219], off
	s_mov_b32 m0, s49
	s_nop 0
	global_load_lds_dwordx4 v[220:221], off
	s_waitcnt vmcnt(8)
	s_waitcnt lgkmcnt(0)
	s_barrier
	s_setprio 1
	s_waitcnt lgkmcnt(0)
	v_mfma_f32_16x16x32_bf16 v[62:65], v[148:151], v[182:185], v[62:65]
	v_mfma_f32_16x16x32_bf16 v[54:57], v[156:159], v[182:185], v[54:57]
	v_mfma_f32_16x16x32_bf16 v[46:49], v[148:151], v[190:193], v[46:49]
	v_mfma_f32_16x16x32_bf16 v[38:41], v[156:159], v[190:193], v[38:41]
	v_mfma_f32_16x16x32_bf16 v[30:33], v[148:151], v[198:201], v[30:33]
	v_mfma_f32_16x16x32_bf16 v[22:25], v[156:159], v[198:201], v[22:25]
	v_mfma_f32_16x16x32_bf16 v[14:17], v[148:151], v[206:209], v[14:17]
	v_mfma_f32_16x16x32_bf16 v[6:9], v[156:159], v[206:209], v[6:9]
	v_mfma_f32_16x16x32_bf16 v[62:65], v[152:155], v[186:189], v[62:65]
	v_mfma_f32_16x16x32_bf16 v[54:57], v[160:163], v[186:189], v[54:57]
	v_mfma_f32_16x16x32_bf16 v[46:49], v[152:155], v[194:197], v[46:49]
	v_mfma_f32_16x16x32_bf16 v[38:41], v[160:163], v[194:197], v[38:41]
	v_mfma_f32_16x16x32_bf16 v[30:33], v[152:155], v[202:205], v[30:33]
	v_mfma_f32_16x16x32_bf16 v[22:25], v[160:163], v[202:205], v[22:25]
	v_mfma_f32_16x16x32_bf16 v[14:17], v[152:155], v[210:213], v[14:17]
	v_mfma_f32_16x16x32_bf16 v[6:9], v[160:163], v[210:213], v[6:9]
	s_setprio 0
	s_setprio 1
	v_mfma_f32_16x16x32_bf16 v[58:61], v[166:169], v[182:185], v[58:61]
	v_mfma_f32_16x16x32_bf16 v[50:53], v[174:177], v[182:185], v[50:53]
	v_mfma_f32_16x16x32_bf16 v[42:45], v[166:169], v[190:193], v[42:45]
	v_mfma_f32_16x16x32_bf16 v[34:37], v[174:177], v[190:193], v[34:37]
	v_mfma_f32_16x16x32_bf16 v[26:29], v[166:169], v[198:201], v[26:29]
	v_mfma_f32_16x16x32_bf16 v[18:21], v[174:177], v[198:201], v[18:21]
	v_mfma_f32_16x16x32_bf16 v[10:13], v[166:169], v[206:209], v[10:13]
	v_mfma_f32_16x16x32_bf16 v[2:5], v[174:177], v[206:209], v[2:5]
	v_mfma_f32_16x16x32_bf16 v[58:61], v[170:173], v[186:189], v[58:61]
	v_mfma_f32_16x16x32_bf16 v[50:53], v[178:181], v[186:189], v[50:53]
	v_mfma_f32_16x16x32_bf16 v[42:45], v[170:173], v[194:197], v[42:45]
	v_mfma_f32_16x16x32_bf16 v[34:37], v[178:181], v[194:197], v[34:37]
	v_mfma_f32_16x16x32_bf16 v[26:29], v[170:173], v[202:205], v[26:29]
	v_mfma_f32_16x16x32_bf16 v[18:21], v[178:181], v[202:205], v[18:21]
	v_mfma_f32_16x16x32_bf16 v[10:13], v[170:173], v[210:213], v[10:13]
	v_mfma_f32_16x16x32_bf16 v[2:5], v[178:181], v[210:213], v[2:5]
	s_setprio 0
	s_barrier
	s_add_i32 s65, 0, 0x18000
	v_add_u32_e32 v147, s65, v142
	s_add_i32 s66, 0, 0x1c000
	ds_read_b128 v[148:151], v147
	ds_read_b128 v[152:155], v147 offset:1024
	ds_read_b128 v[156:159], v147 offset:2048
	ds_read_b128 v[160:163], v147 offset:3072
	v_add_u32_e32 v147, s66, v142
	ds_read_b128 v[166:169], v147
	ds_read_b128 v[170:173], v147 offset:1024
	ds_read_b128 v[174:177], v147 offset:2048
	ds_read_b128 v[178:181], v147 offset:3072
	s_add_u32 s44, s44, 0x40000
	s_addc_u32 s45, s45, 0
	s_mov_b32 m0, s50
	v_lshl_add_u64 v[222:223], s[44:45], 0, v[130:131]
	ds_read_b128 v[182:185], v146 offset:32768
	ds_read_b128 v[186:189], v146 offset:33792
	ds_read_b128 v[190:193], v146 offset:34816
	ds_read_b128 v[194:197], v146 offset:35840
	ds_read_b128 v[198:201], v146 offset:36864
	ds_read_b128 v[202:205], v146 offset:37888
	ds_read_b128 v[206:209], v146 offset:38912
	ds_read_b128 v[210:213], v146 offset:39936
	global_load_lds_dwordx4 v[222:223], off
	v_lshl_add_u64 v[222:223], s[44:45], 0, v[132:133]
	s_mov_b32 m0, s51
	s_nop 0
	global_load_lds_dwordx4 v[222:223], off
	s_waitcnt vmcnt(8)
	s_waitcnt lgkmcnt(0)
	s_barrier
	s_setprio 1
	s_waitcnt lgkmcnt(0)
	v_mfma_f32_16x16x32_bf16 v[126:129], v[148:151], v[182:185], v[126:129]
	v_mfma_f32_16x16x32_bf16 v[118:121], v[156:159], v[182:185], v[118:121]
	v_mfma_f32_16x16x32_bf16 v[110:113], v[148:151], v[190:193], v[110:113]
	v_mfma_f32_16x16x32_bf16 v[102:105], v[156:159], v[190:193], v[102:105]
	v_mfma_f32_16x16x32_bf16 v[94:97], v[148:151], v[198:201], v[94:97]
	v_mfma_f32_16x16x32_bf16 v[86:89], v[156:159], v[198:201], v[86:89]
	v_mfma_f32_16x16x32_bf16 v[78:81], v[148:151], v[206:209], v[78:81]
	v_mfma_f32_16x16x32_bf16 v[70:73], v[156:159], v[206:209], v[70:73]
	v_mfma_f32_16x16x32_bf16 v[126:129], v[152:155], v[186:189], v[126:129]
	v_mfma_f32_16x16x32_bf16 v[118:121], v[160:163], v[186:189], v[118:121]
	v_mfma_f32_16x16x32_bf16 v[110:113], v[152:155], v[194:197], v[110:113]
	v_mfma_f32_16x16x32_bf16 v[102:105], v[160:163], v[194:197], v[102:105]
	v_mfma_f32_16x16x32_bf16 v[94:97], v[152:155], v[202:205], v[94:97]
	v_mfma_f32_16x16x32_bf16 v[86:89], v[160:163], v[202:205], v[86:89]
	v_mfma_f32_16x16x32_bf16 v[78:81], v[152:155], v[210:213], v[78:81]
	v_mfma_f32_16x16x32_bf16 v[70:73], v[160:163], v[210:213], v[70:73]
	s_setprio 0
	s_setprio 1
	v_mfma_f32_16x16x32_bf16 v[122:125], v[166:169], v[182:185], v[122:125]
	v_mfma_f32_16x16x32_bf16 v[114:117], v[174:177], v[182:185], v[114:117]
	v_mfma_f32_16x16x32_bf16 v[106:109], v[166:169], v[190:193], v[106:109]
	v_mfma_f32_16x16x32_bf16 v[98:101], v[174:177], v[190:193], v[98:101]
	v_mfma_f32_16x16x32_bf16 v[90:93], v[166:169], v[198:201], v[90:93]
	v_mfma_f32_16x16x32_bf16 v[82:85], v[174:177], v[198:201], v[82:85]
	v_mfma_f32_16x16x32_bf16 v[74:77], v[166:169], v[206:209], v[74:77]
	v_mfma_f32_16x16x32_bf16 v[66:69], v[174:177], v[206:209], v[66:69]
	v_mfma_f32_16x16x32_bf16 v[122:125], v[170:173], v[186:189], v[122:125]
	v_mfma_f32_16x16x32_bf16 v[114:117], v[178:181], v[186:189], v[114:117]
	v_mfma_f32_16x16x32_bf16 v[106:109], v[170:173], v[194:197], v[106:109]
	v_mfma_f32_16x16x32_bf16 v[98:101], v[178:181], v[194:197], v[98:101]
	v_mfma_f32_16x16x32_bf16 v[90:93], v[170:173], v[202:205], v[90:93]
	v_mfma_f32_16x16x32_bf16 v[82:85], v[178:181], v[202:205], v[82:85]
	v_mfma_f32_16x16x32_bf16 v[74:77], v[170:173], v[210:213], v[74:77]
	v_mfma_f32_16x16x32_bf16 v[66:69], v[178:181], v[210:213], v[66:69]
	s_setprio 0
	s_barrier
	s_add_i32 s44, s65, s46
	v_lshl_add_u64 v[214:215], v[214:215], 0, s[8:9]
	s_mov_b32 m0, s44
	ds_read_b128 v[182:185], v146 offset:49152
	ds_read_b128 v[186:189], v146 offset:50176
	ds_read_b128 v[190:193], v146 offset:51200
	ds_read_b128 v[194:197], v146 offset:52224
	ds_read_b128 v[198:201], v146 offset:53248
	ds_read_b128 v[202:205], v146 offset:54272
	ds_read_b128 v[206:209], v146 offset:55296
	ds_read_b128 v[210:213], v146 offset:56320
	global_load_lds_dwordx4 v[214:215], off
	s_add_i32 m0, s44, 0x2000
	s_add_u32 s36, s36, 0x40080
	v_lshl_add_u64 v[214:215], v[216:217], 0, s[8:9]
	s_addc_u32 s37, s37, 0
	s_add_i32 s44, s66, s46
	global_load_lds_dwordx4 v[214:215], off
	v_lshl_add_u64 v[214:215], s[36:37], 0, v[130:131]
	s_mov_b32 m0, s44
	s_nop 0
	global_load_lds_dwordx4 v[214:215], off
	v_lshl_add_u64 v[214:215], s[36:37], 0, v[132:133]
	s_add_i32 m0, s44, 0x2000
	s_nop 0
	global_load_lds_dwordx4 v[214:215], off
	v_lshl_add_u64 v[214:215], v[218:219], 0, s[8:9]
	s_mov_b32 m0, s54
	s_nop 0
	global_load_lds_dwordx4 v[214:215], off
	v_lshl_add_u64 v[214:215], v[220:221], 0, s[8:9]
	s_mov_b32 m0, s55
	s_nop 0
	global_load_lds_dwordx4 v[214:215], off
	s_waitcnt vmcnt(8)
	s_waitcnt lgkmcnt(0)
	s_barrier
	s_setprio 1
	s_waitcnt lgkmcnt(0)
	v_mfma_f32_16x16x32_bf16 v[62:65], v[148:151], v[182:185], v[62:65]
	v_mfma_f32_16x16x32_bf16 v[54:57], v[156:159], v[182:185], v[54:57]
	v_mfma_f32_16x16x32_bf16 v[46:49], v[148:151], v[190:193], v[46:49]
	v_mfma_f32_16x16x32_bf16 v[38:41], v[156:159], v[190:193], v[38:41]
	v_mfma_f32_16x16x32_bf16 v[30:33], v[148:151], v[198:201], v[30:33]
	v_mfma_f32_16x16x32_bf16 v[22:25], v[156:159], v[198:201], v[22:25]
	v_mfma_f32_16x16x32_bf16 v[14:17], v[148:151], v[206:209], v[14:17]
	v_mfma_f32_16x16x32_bf16 v[6:9], v[156:159], v[206:209], v[6:9]
	v_mfma_f32_16x16x32_bf16 v[62:65], v[152:155], v[186:189], v[62:65]
	v_mfma_f32_16x16x32_bf16 v[54:57], v[160:163], v[186:189], v[54:57]
	v_mfma_f32_16x16x32_bf16 v[46:49], v[152:155], v[194:197], v[46:49]
	v_mfma_f32_16x16x32_bf16 v[38:41], v[160:163], v[194:197], v[38:41]
	v_mfma_f32_16x16x32_bf16 v[30:33], v[152:155], v[202:205], v[30:33]
	v_mfma_f32_16x16x32_bf16 v[22:25], v[160:163], v[202:205], v[22:25]
	v_mfma_f32_16x16x32_bf16 v[14:17], v[152:155], v[210:213], v[14:17]
	v_mfma_f32_16x16x32_bf16 v[6:9], v[160:163], v[210:213], v[6:9]
	s_setprio 0
	s_setprio 1
	v_mfma_f32_16x16x32_bf16 v[58:61], v[166:169], v[182:185], v[58:61]
	v_mfma_f32_16x16x32_bf16 v[50:53], v[174:177], v[182:185], v[50:53]
	v_mfma_f32_16x16x32_bf16 v[42:45], v[166:169], v[190:193], v[42:45]
	v_mfma_f32_16x16x32_bf16 v[34:37], v[174:177], v[190:193], v[34:37]
	v_mfma_f32_16x16x32_bf16 v[26:29], v[166:169], v[198:201], v[26:29]
	v_mfma_f32_16x16x32_bf16 v[18:21], v[174:177], v[198:201], v[18:21]
	v_mfma_f32_16x16x32_bf16 v[10:13], v[166:169], v[206:209], v[10:13]
	v_mfma_f32_16x16x32_bf16 v[2:5], v[174:177], v[206:209], v[2:5]
	v_mfma_f32_16x16x32_bf16 v[58:61], v[170:173], v[186:189], v[58:61]
	v_mfma_f32_16x16x32_bf16 v[50:53], v[178:181], v[186:189], v[50:53]
	v_mfma_f32_16x16x32_bf16 v[42:45], v[170:173], v[194:197], v[42:45]
	v_mfma_f32_16x16x32_bf16 v[34:37], v[178:181], v[194:197], v[34:37]
	v_mfma_f32_16x16x32_bf16 v[26:29], v[170:173], v[202:205], v[26:29]
	v_mfma_f32_16x16x32_bf16 v[18:21], v[178:181], v[202:205], v[18:21]
	v_mfma_f32_16x16x32_bf16 v[10:13], v[170:173], v[210:213], v[10:13]
	v_mfma_f32_16x16x32_bf16 v[2:5], v[178:181], v[210:213], v[2:5]
	s_setprio 0
	s_barrier
	s_add_i32 s64, s64, 2
	s_add_u32 s24, s24, 0x100
	s_addc_u32 s25, s25, 0
	s_add_u32 s62, s62, 0x100
	s_addc_u32 s63, s63, 0
	s_cmp_gt_u32 s64, 13
	s_cbranch_scc0 .LBB0_977
	s_branch .Lt9_post
.Lt9_h0:
	ds_read_b128 v[148:151], v144
	ds_read_b128 v[152:155], v144 offset:1024
	ds_read_b128 v[156:159], v144 offset:2048
	ds_read_b128 v[160:163], v144 offset:3072
	ds_read_b128 v[166:169], v145
	ds_read_b128 v[170:173], v145 offset:1024
	ds_read_b128 v[174:177], v145 offset:2048
	ds_read_b128 v[178:181], v145 offset:3072
	s_add_u32 s36, s24, 0xfffc0080
	s_addc_u32 s37, s25, -1
	s_cmp_eq_u32 s64, 12
	s_cselect_b32 s45, s15, s37
	s_cselect_b32 s44, s60, s36
	s_cselect_b32 s37, s13, s63
	s_cselect_b32 s36, s61, s62
	v_lshl_add_u64 v[214:215], s[24:25], 0, v[134:135]
	s_add_i32 m0, s23, 0xc000
	ds_read_b128 v[182:185], v146
	ds_read_b128 v[186:189], v146 offset:1024
	ds_read_b128 v[190:193], v146 offset:2048
	ds_read_b128 v[194:197], v146 offset:3072
	ds_read_b128 v[198:201], v146 offset:4096
	ds_read_b128 v[202:205], v146 offset:5120
	ds_read_b128 v[206:209], v146 offset:6144
	ds_read_b128 v[210:213], v146 offset:7168
	v_lshl_add_u64 v[214:215], s[24:25], 0, v[136:137]
	s_add_i32 m0, s23, 0xe000
	s_nop 0
	s_waitcnt vmcnt(6)
	s_waitcnt lgkmcnt(0)
	s_barrier
	s_setprio 1
	s_waitcnt lgkmcnt(0)
	v_mfma_f32_16x16x32_bf16 v[126:129], v[148:151], v[182:185], v[126:129]
	v_mfma_f32_16x16x32_bf16 v[118:121], v[156:159], v[182:185], v[118:121]
	v_mfma_f32_16x16x32_bf16 v[110:113], v[148:151], v[190:193], v[110:113]
	v_mfma_f32_16x16x32_bf16 v[102:105], v[156:159], v[190:193], v[102:105]
	v_mfma_f32_16x16x32_bf16 v[94:97], v[148:151], v[198:201], v[94:97]
	v_mfma_f32_16x16x32_bf16 v[86:89], v[156:159], v[198:201], v[86:89]
	v_mfma_f32_16x16x32_bf16 v[78:81], v[148:151], v[206:209], v[78:81]
	v_mfma_f32_16x16x32_bf16 v[70:73], v[156:159], v[206:209], v[70:73]
	v_mfma_f32_16x16x32_bf16 v[126:129], v[152:155], v[186:189], v[126:129]
	v_mfma_f32_16x16x32_bf16 v[118:121], v[160:163], v[186:189], v[118:121]
	v_mfma_f32_16x16x32_bf16 v[110:113], v[152:155], v[194:197], v[110:113]
	v_mfma_f32_16x16x32_bf16 v[102:105], v[160:163], v[194:197], v[102:105]
	v_mfma_f32_16x16x32_bf16 v[94:97], v[152:155], v[202:205], v[94:97]
	v_mfma_f32_16x16x32_bf16 v[86:89], v[160:163], v[202:205], v[86:89]
	v_mfma_f32_16x16x32_bf16 v[78:81], v[152:155], v[210:213], v[78:81]
	v_mfma_f32_16x16x32_bf16 v[70:73], v[160:163], v[210:213], v[70:73]
	s_setprio 0
	s_setprio 1
	v_mfma_f32_16x16x32_bf16 v[122:125], v[166:169], v[182:185], v[122:125]
	v_mfma_f32_16x16x32_bf16 v[114:117], v[174:177], v[182:185], v[114:117]
	v_mfma_f32_16x16x32_bf16 v[106:109], v[166:169], v[190:193], v[106:109]
	v_mfma_f32_16x16x32_bf16 v[98:101], v[174:177], v[190:193], v[98:101]
	v_mfma_f32_16x16x32_bf16 v[90:93], v[166:169], v[198:201], v[90:93]
	v_mfma_f32_16x16x32_bf16 v[82:85], v[174:177], v[198:201], v[82:85]
	v_mfma_f32_16x16x32_bf16 v[74:77], v[166:169], v[206:209], v[74:77]
	v_mfma_f32_16x16x32_bf16 v[66:69], v[174:177], v[206:209], v[66:69]
	v_mfma_f32_16x16x32_bf16 v[122:125], v[170:173], v[186:189], v[122:125]
	v_mfma_f32_16x16x32_bf16 v[114:117], v[178:181], v[186:189], v[114:117]
	v_mfma_f32_16x16x32_bf16 v[106:109], v[170:173], v[194:197], v[106:109]
	v_mfma_f32_16x16x32_bf16 v[98:101], v[178:181], v[194:197], v[98:101]
	v_mfma_f32_16x16x32_bf16 v[90:93], v[170:173], v[202:205], v[90:93]
	v_mfma_f32_16x16x32_bf16 v[82:85], v[178:181], v[202:205], v[82:85]
	v_mfma_f32_16x16x32_bf16 v[74:77], v[170:173], v[210:213], v[74:77]
	v_mfma_f32_16x16x32_bf16 v[66:69], v[178:181], v[210:213], v[66:69]
	s_setprio 0
	s_barrier
	s_add_i32 s65, s56, s46
	v_lshl_add_u64 v[214:215], s[36:37], 0, v[130:131]
	s_mov_b32 m0, s65
	global_load_lds_dwordx4 v[214:215], off
	s_add_i32 m0, s65, 0x2000
	s_add_u32 s66, s36, 0x40000
	v_lshl_add_u64 v[216:217], s[36:37], 0, v[132:133]
	s_addc_u32 s67, s37, 0
	s_add_i32 s65, s57, s46
	global_load_lds_dwordx4 v[216:217], off
	v_lshl_add_u64 v[218:219], s[66:67], 0, v[130:131]
	s_mov_b32 m0, s65
	v_lshl_add_u64 v[220:221], s[44:45], 0, v[132:133]
	global_load_lds_dwordx4 v[218:219], off
	v_lshl_add_u64 v[218:219], s[66:67], 0, v[132:133]
	s_add_i32 m0, s65, 0x2000
	s_nop 0
	global_load_lds_dwordx4 v[218:219], off
	v_lshl_add_u64 v[218:219], s[44:45], 0, v[130:131]
	s_mov_b32 m0, s23
	s_nop 0
	global_load_lds_dwordx4 v[218:219], off
	s_mov_b32 m0, s49
	s_nop 0
	global_load_lds_dwordx4 v[220:221], off
	s_waitcnt vmcnt(6)
	s_waitcnt lgkmcnt(0)
	s_barrier
	s_setprio 1
	s_waitcnt lgkmcnt(0)
	s_setprio 0
	s_setprio 1
	s_setprio 0
	s_barrier
	s_add_i32 s65, 0, 0x18000
	v_add_u32_e32 v147, s65, v142
	s_add_i32 s66, 0, 0x1c000
	ds_read_b128 v[148:151], v147
	ds_read_b128 v[152:155], v147 offset:1024
	ds_read_b128 v[156:159], v147 offset:2048
	ds_read_b128 v[160:163], v147 offset:3072
	v_add_u32_e32 v147, s66, v142
	ds_read_b128 v[166:169], v147
	ds_read_b128 v[170:173], v147 offset:1024
	ds_read_b128 v[174:177], v147 offset:2048
	ds_read_b128 v[178:181], v147 offset:3072
	s_add_u32 s44, s44, 0x40000
	s_addc_u32 s45, s45, 0
	s_mov_b32 m0, s50
	v_lshl_add_u64 v[222:223], s[44:45], 0, v[130:131]
	ds_read_b128 v[182:185], v146 offset:32768
	ds_read_b128 v[186:189], v146 offset:33792
	ds_read_b128 v[190:193], v146 offset:34816
	ds_read_b128 v[194:197], v146 offset:35840
	ds_read_b128 v[198:201], v146 offset:36864
	ds_read_b128 v[202:205], v146 offset:37888
	ds_read_b128 v[206:209], v146 offset:38912
	ds_read_b128 v[210:213], v146 offset:39936
	v_lshl_add_u64 v[222:223], s[44:45], 0, v[132:133]
	s_mov_b32 m0, s51
	s_nop 0
	s_waitcnt vmcnt(6)
	s_waitcnt lgkmcnt(0)
	s_barrier
	s_setprio 1
	s_waitcnt lgkmcnt(0)
	v_mfma_f32_16x16x32_bf16 v[126:129], v[148:151], v[182:185], v[126:129]
	v_mfma_f32_16x16x32_bf16 v[118:121], v[156:159], v[182:185], v[118:121]
	v_mfma_f32_16x16x32_bf16 v[110:113], v[148:151], v[190:193], v[110:113]
	v_mfma_f32_16x16x32_bf16 v[102:105], v[156:159], v[190:193], v[102:105]
	v_mfma_f32_16x16x32_bf16 v[94:97], v[148:151], v[198:201], v[94:97]
	v_mfma_f32_16x16x32_bf16 v[86:89], v[156:159], v[198:201], v[86:89]
	v_mfma_f32_16x16x32_bf16 v[78:81], v[148:151], v[206:209], v[78:81]
	v_mfma_f32_16x16x32_bf16 v[70:73], v[156:159], v[206:209], v[70:73]
	v_mfma_f32_16x16x32_bf16 v[126:129], v[152:155], v[186:189], v[126:129]
	v_mfma_f32_16x16x32_bf16 v[118:121], v[160:163], v[186:189], v[118:121]
	v_mfma_f32_16x16x32_bf16 v[110:113], v[152:155], v[194:197], v[110:113]
	v_mfma_f32_16x16x32_bf16 v[102:105], v[160:163], v[194:197], v[102:105]
	v_mfma_f32_16x16x32_bf16 v[94:97], v[152:155], v[202:205], v[94:97]
	v_mfma_f32_16x16x32_bf16 v[86:89], v[160:163], v[202:205], v[86:89]
	v_mfma_f32_16x16x32_bf16 v[78:81], v[152:155], v[210:213], v[78:81]
	v_mfma_f32_16x16x32_bf16 v[70:73], v[160:163], v[210:213], v[70:73]
	s_setprio 0
	s_setprio 1
	v_mfma_f32_16x16x32_bf16 v[122:125], v[166:169], v[182:185], v[122:125]
	v_mfma_f32_16x16x32_bf16 v[114:117], v[174:177], v[182:185], v[114:117]
	v_mfma_f32_16x16x32_bf16 v[106:109], v[166:169], v[190:193], v[106:109]
	v_mfma_f32_16x16x32_bf16 v[98:101], v[174:177], v[190:193], v[98:101]
	v_mfma_f32_16x16x32_bf16 v[90:93], v[166:169], v[198:201], v[90:93]
	v_mfma_f32_16x16x32_bf16 v[82:85], v[174:177], v[198:201], v[82:85]
	v_mfma_f32_16x16x32_bf16 v[74:77], v[166:169], v[206:209], v[74:77]
	v_mfma_f32_16x16x32_bf16 v[66:69], v[174:177], v[206:209], v[66:69]
	v_mfma_f32_16x16x32_bf16 v[122:125], v[170:173], v[186:189], v[122:125]
	v_mfma_f32_16x16x32_bf16 v[114:117], v[178:181], v[186:189], v[114:117]
	v_mfma_f32_16x16x32_bf16 v[106:109], v[170:173], v[194:197], v[106:109]
	v_mfma_f32_16x16x32_bf16 v[98:101], v[178:181], v[194:197], v[98:101]
	v_mfma_f32_16x16x32_bf16 v[90:93], v[170:173], v[202:205], v[90:93]
	v_mfma_f32_16x16x32_bf16 v[82:85], v[178:181], v[202:205], v[82:85]
	v_mfma_f32_16x16x32_bf16 v[74:77], v[170:173], v[210:213], v[74:77]
	v_mfma_f32_16x16x32_bf16 v[66:69], v[178:181], v[210:213], v[66:69]
	s_setprio 0
	s_barrier
	s_add_i32 s44, s65, s46
	v_lshl_add_u64 v[214:215], v[214:215], 0, s[8:9]
	s_mov_b32 m0, s44
	global_load_lds_dwordx4 v[214:215], off
	s_add_i32 m0, s44, 0x2000
	s_add_u32 s36, s36, 0x40080
	v_lshl_add_u64 v[214:215], v[216:217], 0, s[8:9]
	s_addc_u32 s37, s37, 0
	s_add_i32 s44, s66, s46
	global_load_lds_dwordx4 v[214:215], off
	v_lshl_add_u64 v[214:215], s[36:37], 0, v[130:131]
	s_mov_b32 m0, s44
	s_nop 0
	global_load_lds_dwordx4 v[214:215], off
	v_lshl_add_u64 v[214:215], s[36:37], 0, v[132:133]
	s_add_i32 m0, s44, 0x2000
	s_nop 0
	global_load_lds_dwordx4 v[214:215], off
	v_lshl_add_u64 v[214:215], v[218:219], 0, s[8:9]
	s_mov_b32 m0, s54
	s_nop 0
	global_load_lds_dwordx4 v[214:215], off
	v_lshl_add_u64 v[214:215], v[220:221], 0, s[8:9]
	s_mov_b32 m0, s55
	s_nop 0
	global_load_lds_dwordx4 v[214:215], off
	s_waitcnt vmcnt(6)
	s_waitcnt lgkmcnt(0)
	s_barrier
	s_setprio 1
	s_waitcnt lgkmcnt(0)
	s_setprio 0
	s_setprio 1
	s_setprio 0
	s_barrier
	s_add_i32 s64, s64, 2
	s_add_u32 s24, s24, 0x100
	s_addc_u32 s25, s25, 0
	s_add_u32 s62, s62, 0x100
	s_addc_u32 s63, s63, 0
	s_cmp_gt_u32 s64, 13
	s_cbranch_scc0 .Lt9_h0
	s_branch .Lt9_post
.Lt9_h1:
	ds_read_b128 v[148:151], v144
	ds_read_b128 v[152:155], v144 offset:1024
	ds_read_b128 v[156:159], v144 offset:2048
	ds_read_b128 v[160:163], v144 offset:3072
	ds_read_b128 v[166:169], v145
	ds_read_b128 v[170:173], v145 offset:1024
	ds_read_b128 v[174:177], v145 offset:2048
	ds_read_b128 v[178:181], v145 offset:3072
	s_add_u32 s36, s24, 0xfffc0080
	s_addc_u32 s37, s25, -1
	s_cmp_eq_u32 s64, 12
	s_cselect_b32 s45, s15, s37
	s_cselect_b32 s44, s60, s36
	s_cselect_b32 s37, s13, s63
	s_cselect_b32 s36, s61, s62
	v_lshl_add_u64 v[214:215], s[24:25], 0, v[134:135]
	s_add_i32 m0, s23, 0xc000
	global_load_lds_dwordx4 v[214:215], off
	v_lshl_add_u64 v[214:215], s[24:25], 0, v[136:137]
	s_add_i32 m0, s23, 0xe000
	s_nop 0
	global_load_lds_dwordx4 v[214:215], off
	s_waitcnt vmcnt(6)
	s_waitcnt lgkmcnt(0)
	s_barrier
	s_setprio 1
	s_waitcnt lgkmcnt(0)
	s_setprio 0
	s_setprio 1
	s_setprio 0
	s_barrier
	s_add_i32 s65, s56, s46
	v_lshl_add_u64 v[214:215], s[36:37], 0, v[130:131]
	s_mov_b32 m0, s65
	ds_read_b128 v[182:185], v146 offset:16384
	ds_read_b128 v[186:189], v146 offset:17408
	ds_read_b128 v[190:193], v146 offset:18432
	ds_read_b128 v[194:197], v146 offset:19456
	ds_read_b128 v[198:201], v146 offset:20480
	ds_read_b128 v[202:205], v146 offset:21504
	ds_read_b128 v[206:209], v146 offset:22528
	ds_read_b128 v[210:213], v146 offset:23552
	global_load_lds_dwordx4 v[214:215], off
	s_add_i32 m0, s65, 0x2000
	s_add_u32 s66, s36, 0x40000
	v_lshl_add_u64 v[216:217], s[36:37], 0, v[132:133]
	s_addc_u32 s67, s37, 0
	s_add_i32 s65, s57, s46
	global_load_lds_dwordx4 v[216:217], off
	v_lshl_add_u64 v[218:219], s[66:67], 0, v[130:131]
	s_mov_b32 m0, s65
	v_lshl_add_u64 v[220:221], s[44:45], 0, v[132:133]
	global_load_lds_dwordx4 v[218:219], off
	v_lshl_add_u64 v[218:219], s[66:67], 0, v[132:133]
	s_add_i32 m0, s65, 0x2000
	s_nop 0
	global_load_lds_dwordx4 v[218:219], off
	v_lshl_add_u64 v[218:219], s[44:45], 0, v[130:131]
	s_mov_b32 m0, s23
	s_nop 0
	s_mov_b32 m0, s49
	s_nop 0
	s_waitcnt vmcnt(6)
	s_waitcnt lgkmcnt(0)
	s_barrier
	s_setprio 1
	s_waitcnt lgkmcnt(0)
	v_mfma_f32_16x16x32_bf16 v[62:65], v[148:151], v[182:185], v[62:65]
	v_mfma_f32_16x16x32_bf16 v[54:57], v[156:159], v[182:185], v[54:57]
	v_mfma_f32_16x16x32_bf16 v[46:49], v[148:151], v[190:193], v[46:49]
	v_mfma_f32_16x16x32_bf16 v[38:41], v[156:159], v[190:193], v[38:41]
	v_mfma_f32_16x16x32_bf16 v[30:33], v[148:151], v[198:201], v[30:33]
	v_mfma_f32_16x16x32_bf16 v[22:25], v[156:159], v[198:201], v[22:25]
	v_mfma_f32_16x16x32_bf16 v[14:17], v[148:151], v[206:209], v[14:17]
	v_mfma_f32_16x16x32_bf16 v[6:9], v[156:159], v[206:209], v[6:9]
	v_mfma_f32_16x16x32_bf16 v[62:65], v[152:155], v[186:189], v[62:65]
	v_mfma_f32_16x16x32_bf16 v[54:57], v[160:163], v[186:189], v[54:57]
	v_mfma_f32_16x16x32_bf16 v[46:49], v[152:155], v[194:197], v[46:49]
	v_mfma_f32_16x16x32_bf16 v[38:41], v[160:163], v[194:197], v[38:41]
	v_mfma_f32_16x16x32_bf16 v[30:33], v[152:155], v[202:205], v[30:33]
	v_mfma_f32_16x16x32_bf16 v[22:25], v[160:163], v[202:205], v[22:25]
	v_mfma_f32_16x16x32_bf16 v[14:17], v[152:155], v[210:213], v[14:17]
	v_mfma_f32_16x16x32_bf16 v[6:9], v[160:163], v[210:213], v[6:9]
	s_setprio 0
	s_setprio 1
	v_mfma_f32_16x16x32_bf16 v[58:61], v[166:169], v[182:185], v[58:61]
	v_mfma_f32_16x16x32_bf16 v[50:53], v[174:177], v[182:185], v[50:53]
	v_mfma_f32_16x16x32_bf16 v[42:45], v[166:169], v[190:193], v[42:45]
	v_mfma_f32_16x16x32_bf16 v[34:37], v[174:177], v[190:193], v[34:37]
	v_mfma_f32_16x16x32_bf16 v[26:29], v[166:169], v[198:201], v[26:29]
	v_mfma_f32_16x16x32_bf16 v[18:21], v[174:177], v[198:201], v[18:21]
	v_mfma_f32_16x16x32_bf16 v[10:13], v[166:169], v[206:209], v[10:13]
	v_mfma_f32_16x16x32_bf16 v[2:5], v[174:177], v[206:209], v[2:5]
	v_mfma_f32_16x16x32_bf16 v[58:61], v[170:173], v[186:189], v[58:61]
	v_mfma_f32_16x16x32_bf16 v[50:53], v[178:181], v[186:189], v[50:53]
	v_mfma_f32_16x16x32_bf16 v[42:45], v[170:173], v[194:197], v[42:45]
	v_mfma_f32_16x16x32_bf16 v[34:37], v[178:181], v[194:197], v[34:37]
	v_mfma_f32_16x16x32_bf16 v[26:29], v[170:173], v[202:205], v[26:29]
	v_mfma_f32_16x16x32_bf16 v[18:21], v[178:181], v[202:205], v[18:21]
	v_mfma_f32_16x16x32_bf16 v[10:13], v[170:173], v[210:213], v[10:13]
	v_mfma_f32_16x16x32_bf16 v[2:5], v[178:181], v[210:213], v[2:5]
	s_setprio 0
	s_barrier
	s_add_i32 s65, 0, 0x18000
	v_add_u32_e32 v147, s65, v142
	s_add_i32 s66, 0, 0x1c000
	ds_read_b128 v[148:151], v147
	ds_read_b128 v[152:155], v147 offset:1024
	ds_read_b128 v[156:159], v147 offset:2048
	ds_read_b128 v[160:163], v147 offset:3072
	v_add_u32_e32 v147, s66, v142
	ds_read_b128 v[166:169], v147
	ds_read_b128 v[170:173], v147 offset:1024
	ds_read_b128 v[174:177], v147 offset:2048
	ds_read_b128 v[178:181], v147 offset:3072
	s_add_u32 s44, s44, 0x40000
	s_addc_u32 s45, s45, 0
	s_mov_b32 m0, s50
	v_lshl_add_u64 v[222:223], s[44:45], 0, v[130:131]
	global_load_lds_dwordx4 v[222:223], off
	v_lshl_add_u64 v[222:223], s[44:45], 0, v[132:133]
	s_mov_b32 m0, s51
	s_nop 0
	global_load_lds_dwordx4 v[222:223], off
	s_waitcnt vmcnt(6)
	s_waitcnt lgkmcnt(0)
	s_barrier
	s_setprio 1
	s_waitcnt lgkmcnt(0)
	s_setprio 0
	s_setprio 1
	s_setprio 0
	s_barrier
	s_add_i32 s44, s65, s46
	v_lshl_add_u64 v[214:215], v[214:215], 0, s[8:9]
	s_mov_b32 m0, s44
	ds_read_b128 v[182:185], v146 offset:49152
	ds_read_b128 v[186:189], v146 offset:50176
	ds_read_b128 v[190:193], v146 offset:51200
	ds_read_b128 v[194:197], v146 offset:52224
	ds_read_b128 v[198:201], v146 offset:53248
	ds_read_b128 v[202:205], v146 offset:54272
	ds_read_b128 v[206:209], v146 offset:55296
	ds_read_b128 v[210:213], v146 offset:56320
	global_load_lds_dwordx4 v[214:215], off
	s_add_i32 m0, s44, 0x2000
	s_add_u32 s36, s36, 0x40080
	v_lshl_add_u64 v[214:215], v[216:217], 0, s[8:9]
	s_addc_u32 s37, s37, 0
	s_add_i32 s44, s66, s46
	global_load_lds_dwordx4 v[214:215], off
	v_lshl_add_u64 v[214:215], s[36:37], 0, v[130:131]
	s_mov_b32 m0, s44
	s_nop 0
	global_load_lds_dwordx4 v[214:215], off
	v_lshl_add_u64 v[214:215], s[36:37], 0, v[132:133]
	s_add_i32 m0, s44, 0x2000
	s_nop 0
	global_load_lds_dwordx4 v[214:215], off
	v_lshl_add_u64 v[214:215], v[218:219], 0, s[8:9]
	s_mov_b32 m0, s54
	s_nop 0
	v_lshl_add_u64 v[214:215], v[220:221], 0, s[8:9]
	s_mov_b32 m0, s55
	s_nop 0
	s_waitcnt vmcnt(6)
	s_waitcnt lgkmcnt(0)
	s_barrier
	s_setprio 1
	s_waitcnt lgkmcnt(0)
	v_mfma_f32_16x16x32_bf16 v[62:65], v[148:151], v[182:185], v[62:65]
	v_mfma_f32_16x16x32_bf16 v[54:57], v[156:159], v[182:185], v[54:57]
	v_mfma_f32_16x16x32_bf16 v[46:49], v[148:151], v[190:193], v[46:49]
	v_mfma_f32_16x16x32_bf16 v[38:41], v[156:159], v[190:193], v[38:41]
	v_mfma_f32_16x16x32_bf16 v[30:33], v[148:151], v[198:201], v[30:33]
	v_mfma_f32_16x16x32_bf16 v[22:25], v[156:159], v[198:201], v[22:25]
	v_mfma_f32_16x16x32_bf16 v[14:17], v[148:151], v[206:209], v[14:17]
	v_mfma_f32_16x16x32_bf16 v[6:9], v[156:159], v[206:209], v[6:9]
	v_mfma_f32_16x16x32_bf16 v[62:65], v[152:155], v[186:189], v[62:65]
	v_mfma_f32_16x16x32_bf16 v[54:57], v[160:163], v[186:189], v[54:57]
	v_mfma_f32_16x16x32_bf16 v[46:49], v[152:155], v[194:197], v[46:49]
	v_mfma_f32_16x16x32_bf16 v[38:41], v[160:163], v[194:197], v[38:41]
	v_mfma_f32_16x16x32_bf16 v[30:33], v[152:155], v[202:205], v[30:33]
	v_mfma_f32_16x16x32_bf16 v[22:25], v[160:163], v[202:205], v[22:25]
	v_mfma_f32_16x16x32_bf16 v[14:17], v[152:155], v[210:213], v[14:17]
	v_mfma_f32_16x16x32_bf16 v[6:9], v[160:163], v[210:213], v[6:9]
	s_setprio 0
	s_setprio 1
	v_mfma_f32_16x16x32_bf16 v[58:61], v[166:169], v[182:185], v[58:61]
	v_mfma_f32_16x16x32_bf16 v[50:53], v[174:177], v[182:185], v[50:53]
	v_mfma_f32_16x16x32_bf16 v[42:45], v[166:169], v[190:193], v[42:45]
	v_mfma_f32_16x16x32_bf16 v[34:37], v[174:177], v[190:193], v[34:37]
	v_mfma_f32_16x16x32_bf16 v[26:29], v[166:169], v[198:201], v[26:29]
	v_mfma_f32_16x16x32_bf16 v[18:21], v[174:177], v[198:201], v[18:21]
	v_mfma_f32_16x16x32_bf16 v[10:13], v[166:169], v[206:209], v[10:13]
	v_mfma_f32_16x16x32_bf16 v[2:5], v[174:177], v[206:209], v[2:5]
	v_mfma_f32_16x16x32_bf16 v[58:61], v[170:173], v[186:189], v[58:61]
	v_mfma_f32_16x16x32_bf16 v[50:53], v[178:181], v[186:189], v[50:53]
	v_mfma_f32_16x16x32_bf16 v[42:45], v[170:173], v[194:197], v[42:45]
	v_mfma_f32_16x16x32_bf16 v[34:37], v[178:181], v[194:197], v[34:37]
	v_mfma_f32_16x16x32_bf16 v[26:29], v[170:173], v[202:205], v[26:29]
	v_mfma_f32_16x16x32_bf16 v[18:21], v[178:181], v[202:205], v[18:21]
	v_mfma_f32_16x16x32_bf16 v[10:13], v[170:173], v[210:213], v[10:13]
	v_mfma_f32_16x16x32_bf16 v[2:5], v[178:181], v[210:213], v[2:5]
	s_setprio 0
	s_barrier
	s_add_i32 s64, s64, 2
	s_add_u32 s24, s24, 0x100
	s_addc_u32 s25, s25, 0
	s_add_u32 s62, s62, 0x100
	s_addc_u32 s63, s63, 0
	s_cmp_gt_u32 s64, 13
	s_cbranch_scc0 .Lt9_h1

.LBB0_980:
	s_mov_b32 s100, 0xbfb8aa3b
	v_lshl_or_b32 v166, s59, 7, v143
	v_lshl_add_u32 v168, s22, 8, v1
	v_ashrrev_i32_e32 v167, 31, v166
	v_mov_b64_e32 v[170:171], s[40:41]
	v_mad_i64_i32 v[170:171], s[24:25], v168, s58, v[170:171]
	v_lshlrev_b64 v[166:167], 1, v[166:167]
	s_lshl_b32 s98, s58, 4
	s_mov_b32 s99, 0
	v_lshl_add_u64 v[170:171], v[170:171], 0, v[166:167]
	s_lshl_b32 s96, s58, 7
	s_mov_b32 s97, 0
	v_lshl_add_u64 v[172:173], v[170:171], 0, s[96:97]
	s_cmp_eq_u32 s101, 2
	s_cbranch_scc1 .Lt9_g4
	v_pk_mul_f32 v[148:149], v[126:127], s[100:101] op_sel_hi:[1,0]
	v_pk_mul_f32 v[150:151], v[128:129], s[100:101] op_sel_hi:[1,0]
	v_pk_mul_f32 v[152:153], v[118:119], s[100:101] op_sel_hi:[1,0]
	v_pk_mul_f32 v[154:155], v[120:121], s[100:101] op_sel_hi:[1,0]
	v_exp_f32_e32 v148, v148
	v_exp_f32_e32 v149, v149
	v_exp_f32_e32 v150, v150
	v_exp_f32_e32 v151, v151
	v_exp_f32_e32 v152, v152
	v_exp_f32_e32 v153, v153
	v_exp_f32_e32 v154, v154
	v_exp_f32_e32 v155, v155
	v_pk_mul_f32 v[126:127], v[126:127], v[122:123]
	v_pk_mul_f32 v[128:129], v[128:129], v[124:125]
	v_pk_mul_f32 v[118:119], v[118:119], v[114:115]
	v_pk_mul_f32 v[120:121], v[120:121], v[116:117]
	v_pk_add_f32 v[148:149], v[148:149], 1.0 op_sel_hi:[1,0]
	v_pk_add_f32 v[150:151], v[150:151], 1.0 op_sel_hi:[1,0]
	v_pk_add_f32 v[152:153], v[152:153], 1.0 op_sel_hi:[1,0]
	v_pk_add_f32 v[154:155], v[154:155], 1.0 op_sel_hi:[1,0]
	v_rcp_f32_e32 v148, v148
	v_rcp_f32_e32 v149, v149
	v_rcp_f32_e32 v150, v150
	v_rcp_f32_e32 v151, v151
	v_rcp_f32_e32 v152, v152
	v_rcp_f32_e32 v153, v153
	v_rcp_f32_e32 v154, v154
	v_rcp_f32_e32 v155, v155
	s_nop 0
	v_pk_mul_f32 v[126:127], v[148:149], v[126:127]
	v_pk_mul_f32 v[128:129], v[150:151], v[128:129]
	v_pk_mul_f32 v[118:119], v[152:153], v[118:119]
	v_pk_mul_f32 v[120:121], v[154:155], v[120:121]
	v_cvt_pk_bf16_f32 v122, v126, v127
	v_cvt_pk_bf16_f32 v123, v128, v129
	v_cvt_pk_bf16_f32 v124, v118, v119
	v_cvt_pk_bf16_f32 v125, v120, v121
	global_store_dwordx4 v[170:171], v[122:125], off sc1
	v_lshl_add_u64 v[170:171], v[170:171], 0, s[98:99]
	v_pk_mul_f32 v[156:157], v[110:111], s[100:101] op_sel_hi:[1,0]
	v_pk_mul_f32 v[158:159], v[112:113], s[100:101] op_sel_hi:[1,0]
	v_pk_mul_f32 v[160:161], v[102:103], s[100:101] op_sel_hi:[1,0]
	v_pk_mul_f32 v[162:163], v[104:105], s[100:101] op_sel_hi:[1,0]
	v_exp_f32_e32 v156, v156
	v_exp_f32_e32 v157, v157
	v_exp_f32_e32 v158, v158
	v_exp_f32_e32 v159, v159
	v_exp_f32_e32 v160, v160
	v_exp_f32_e32 v161, v161
	v_exp_f32_e32 v162, v162
	v_exp_f32_e32 v163, v163
	v_pk_mul_f32 v[110:111], v[110:111], v[106:107]
	v_pk_mul_f32 v[112:113], v[112:113], v[108:109]
	v_pk_mul_f32 v[102:103], v[102:103], v[98:99]
	v_pk_mul_f32 v[104:105], v[104:105], v[100:101]
	v_pk_add_f32 v[156:157], v[156:157], 1.0 op_sel_hi:[1,0]
	v_pk_add_f32 v[158:159], v[158:159], 1.0 op_sel_hi:[1,0]
	v_pk_add_f32 v[160:161], v[160:161], 1.0 op_sel_hi:[1,0]
	v_pk_add_f32 v[162:163], v[162:163], 1.0 op_sel_hi:[1,0]
	v_rcp_f32_e32 v156, v156
	v_rcp_f32_e32 v157, v157
	v_rcp_f32_e32 v158, v158
	v_rcp_f32_e32 v159, v159
	v_rcp_f32_e32 v160, v160
	v_rcp_f32_e32 v161, v161
	v_rcp_f32_e32 v162, v162
	v_rcp_f32_e32 v163, v163
	s_nop 0
	v_pk_mul_f32 v[110:111], v[156:157], v[110:111]
	v_pk_mul_f32 v[112:113], v[158:159], v[112:113]
	v_pk_mul_f32 v[102:103], v[160:161], v[102:103]
	v_pk_mul_f32 v[104:105], v[162:163], v[104:105]
	v_cvt_pk_bf16_f32 v106, v110, v111
	v_cvt_pk_bf16_f32 v107, v112, v113
	v_cvt_pk_bf16_f32 v108, v102, v103
	v_cvt_pk_bf16_f32 v109, v104, v105
	global_store_dwordx4 v[170:171], v[106:109], off sc1
	v_lshl_add_u64 v[170:171], v[170:171], 0, s[98:99]
	v_pk_mul_f32 v[148:149], v[94:95], s[100:101] op_sel_hi:[1,0]
	v_pk_mul_f32 v[150:151], v[96:97], s[100:101] op_sel_hi:[1,0]
	v_pk_mul_f32 v[152:153], v[86:87], s[100:101] op_sel_hi:[1,0]
	v_pk_mul_f32 v[154:155], v[88:89], s[100:101] op_sel_hi:[1,0]
	v_exp_f32_e32 v148, v148
	v_exp_f32_e32 v149, v149
	v_exp_f32_e32 v150, v150
	v_exp_f32_e32 v151, v151
	v_exp_f32_e32 v152, v152
	v_exp_f32_e32 v153, v153
	v_exp_f32_e32 v154, v154
	v_exp_f32_e32 v155, v155
	v_pk_mul_f32 v[94:95], v[94:95], v[90:91]
	v_pk_mul_f32 v[96:97], v[96:97], v[92:93]
	v_pk_mul_f32 v[86:87], v[86:87], v[82:83]
	v_pk_mul_f32 v[88:89], v[88:89], v[84:85]
	v_pk_add_f32 v[148:149], v[148:149], 1.0 op_sel_hi:[1,0]
	v_pk_add_f32 v[150:151], v[150:151], 1.0 op_sel_hi:[1,0]
	v_pk_add_f32 v[152:153], v[152:153], 1.0 op_sel_hi:[1,0]
	v_pk_add_f32 v[154:155], v[154:155], 1.0 op_sel_hi:[1,0]
	v_rcp_f32_e32 v148, v148
	v_rcp_f32_e32 v149, v149
	v_rcp_f32_e32 v150, v150
	v_rcp_f32_e32 v151, v151
	v_rcp_f32_e32 v152, v152
	v_rcp_f32_e32 v153, v153
	v_rcp_f32_e32 v154, v154
	v_rcp_f32_e32 v155, v155
	s_nop 0
	v_pk_mul_f32 v[94:95], v[148:149], v[94:95]
	v_pk_mul_f32 v[96:97], v[150:151], v[96:97]
	v_pk_mul_f32 v[86:87], v[152:153], v[86:87]
	v_pk_mul_f32 v[88:89], v[154:155], v[88:89]
	v_cvt_pk_bf16_f32 v90, v94, v95
	v_cvt_pk_bf16_f32 v91, v96, v97
	v_cvt_pk_bf16_f32 v92, v86, v87
	v_cvt_pk_bf16_f32 v93, v88, v89
	global_store_dwordx4 v[170:171], v[90:93], off sc1
	v_lshl_add_u64 v[170:171], v[170:171], 0, s[98:99]
	v_pk_mul_f32 v[156:157], v[78:79], s[100:101] op_sel_hi:[1,0]
	v_pk_mul_f32 v[158:159], v[80:81], s[100:101] op_sel_hi:[1,0]
	v_pk_mul_f32 v[160:161], v[70:71], s[100:101] op_sel_hi:[1,0]
	v_pk_mul_f32 v[162:163], v[72:73], s[100:101] op_sel_hi:[1,0]
	v_exp_f32_e32 v156, v156
	v_exp_f32_e32 v157, v157
	v_exp_f32_e32 v158, v158
	v_exp_f32_e32 v159, v159
	v_exp_f32_e32 v160, v160
	v_exp_f32_e32 v161, v161
	v_exp_f32_e32 v162, v162
	v_exp_f32_e32 v163, v163
	v_pk_mul_f32 v[78:79], v[78:79], v[74:75]
	v_pk_mul_f32 v[80:81], v[80:81], v[76:77]
	v_pk_mul_f32 v[70:71], v[70:71], v[66:67]
	v_pk_mul_f32 v[72:73], v[72:73], v[68:69]
	v_pk_add_f32 v[156:157], v[156:157], 1.0 op_sel_hi:[1,0]
	v_pk_add_f32 v[158:159], v[158:159], 1.0 op_sel_hi:[1,0]
	v_pk_add_f32 v[160:161], v[160:161], 1.0 op_sel_hi:[1,0]
	v_pk_add_f32 v[162:163], v[162:163], 1.0 op_sel_hi:[1,0]
	v_rcp_f32_e32 v156, v156
	v_rcp_f32_e32 v157, v157
	v_rcp_f32_e32 v158, v158
	v_rcp_f32_e32 v159, v159
	v_rcp_f32_e32 v160, v160
	v_rcp_f32_e32 v161, v161
	v_rcp_f32_e32 v162, v162
	v_rcp_f32_e32 v163, v163
	s_nop 0
	v_pk_mul_f32 v[78:79], v[156:157], v[78:79]
	v_pk_mul_f32 v[80:81], v[158:159], v[80:81]
	v_pk_mul_f32 v[70:71], v[160:161], v[70:71]
	v_pk_mul_f32 v[72:73], v[162:163], v[72:73]
	v_cvt_pk_bf16_f32 v74, v78, v79
	v_cvt_pk_bf16_f32 v75, v80, v81
	v_cvt_pk_bf16_f32 v76, v70, v71
	v_cvt_pk_bf16_f32 v77, v72, v73
	global_store_dwordx4 v[170:171], v[74:77], off sc1
	s_cmp_eq_u32 s101, 1
	s_cbranch_scc1 .Lt9_eend
.Lt9_g4:
	v_pk_mul_f32 v[148:149], v[62:63], s[100:101] op_sel_hi:[1,0]
	v_pk_mul_f32 v[150:151], v[64:65], s[100:101] op_sel_hi:[1,0]
	v_pk_mul_f32 v[152:153], v[54:55], s[100:101] op_sel_hi:[1,0]
	v_pk_mul_f32 v[154:155], v[56:57], s[100:101] op_sel_hi:[1,0]
	v_exp_f32_e32 v148, v148
	v_exp_f32_e32 v149, v149
	v_exp_f32_e32 v150, v150
	v_exp_f32_e32 v151, v151
	v_exp_f32_e32 v152, v152
	v_exp_f32_e32 v153, v153
	v_exp_f32_e32 v154, v154
	v_exp_f32_e32 v155, v155
	v_pk_mul_f32 v[62:63], v[62:63], v[58:59]
	v_pk_mul_f32 v[64:65], v[64:65], v[60:61]
	v_pk_mul_f32 v[54:55], v[54:55], v[50:51]
	v_pk_mul_f32 v[56:57], v[56:57], v[52:53]
	v_pk_add_f32 v[148:149], v[148:149], 1.0 op_sel_hi:[1,0]
	v_pk_add_f32 v[150:151], v[150:151], 1.0 op_sel_hi:[1,0]
	v_pk_add_f32 v[152:153], v[152:153], 1.0 op_sel_hi:[1,0]
	v_pk_add_f32 v[154:155], v[154:155], 1.0 op_sel_hi:[1,0]
	v_rcp_f32_e32 v148, v148
	v_rcp_f32_e32 v149, v149
	v_rcp_f32_e32 v150, v150
	v_rcp_f32_e32 v151, v151
	v_rcp_f32_e32 v152, v152
	v_rcp_f32_e32 v153, v153
	v_rcp_f32_e32 v154, v154
	v_rcp_f32_e32 v155, v155
	s_nop 0
	v_pk_mul_f32 v[62:63], v[148:149], v[62:63]
	v_pk_mul_f32 v[64:65], v[150:151], v[64:65]
	v_pk_mul_f32 v[54:55], v[152:153], v[54:55]
	v_pk_mul_f32 v[56:57], v[154:155], v[56:57]
	v_cvt_pk_bf16_f32 v58, v62, v63
	v_cvt_pk_bf16_f32 v59, v64, v65
	v_cvt_pk_bf16_f32 v60, v54, v55
	v_cvt_pk_bf16_f32 v61, v56, v57
	global_store_dwordx4 v[172:173], v[58:61], off sc1
	v_lshl_add_u64 v[172:173], v[172:173], 0, s[98:99]
	v_pk_mul_f32 v[156:157], v[46:47], s[100:101] op_sel_hi:[1,0]
	v_pk_mul_f32 v[158:159], v[48:49], s[100:101] op_sel_hi:[1,0]
	v_pk_mul_f32 v[160:161], v[38:39], s[100:101] op_sel_hi:[1,0]
	v_pk_mul_f32 v[162:163], v[40:41], s[100:101] op_sel_hi:[1,0]
	v_exp_f32_e32 v156, v156
	v_exp_f32_e32 v157, v157
	v_exp_f32_e32 v158, v158
	v_exp_f32_e32 v159, v159
	v_exp_f32_e32 v160, v160
	v_exp_f32_e32 v161, v161
	v_exp_f32_e32 v162, v162
	v_exp_f32_e32 v163, v163
	v_pk_mul_f32 v[46:47], v[46:47], v[42:43]
	v_pk_mul_f32 v[48:49], v[48:49], v[44:45]
	v_pk_mul_f32 v[38:39], v[38:39], v[34:35]
	v_pk_mul_f32 v[40:41], v[40:41], v[36:37]
	v_pk_add_f32 v[156:157], v[156:157], 1.0 op_sel_hi:[1,0]
	v_pk_add_f32 v[158:159], v[158:159], 1.0 op_sel_hi:[1,0]
	v_pk_add_f32 v[160:161], v[160:161], 1.0 op_sel_hi:[1,0]
	v_pk_add_f32 v[162:163], v[162:163], 1.0 op_sel_hi:[1,0]
	v_rcp_f32_e32 v156, v156
	v_rcp_f32_e32 v157, v157
	v_rcp_f32_e32 v158, v158
	v_rcp_f32_e32 v159, v159
	v_rcp_f32_e32 v160, v160
	v_rcp_f32_e32 v161, v161
	v_rcp_f32_e32 v162, v162
	v_rcp_f32_e32 v163, v163
	s_nop 0
	v_pk_mul_f32 v[46:47], v[156:157], v[46:47]
	v_pk_mul_f32 v[48:49], v[158:159], v[48:49]
	v_pk_mul_f32 v[38:39], v[160:161], v[38:39]
	v_pk_mul_f32 v[40:41], v[162:163], v[40:41]
	v_cvt_pk_bf16_f32 v42, v46, v47
	v_cvt_pk_bf16_f32 v43, v48, v49
	v_cvt_pk_bf16_f32 v44, v38, v39
	v_cvt_pk_bf16_f32 v45, v40, v41
	global_store_dwordx4 v[172:173], v[42:45], off sc1
	v_lshl_add_u64 v[172:173], v[172:173], 0, s[98:99]
	v_pk_mul_f32 v[148:149], v[30:31], s[100:101] op_sel_hi:[1,0]
	v_pk_mul_f32 v[150:151], v[32:33], s[100:101] op_sel_hi:[1,0]
	v_pk_mul_f32 v[152:153], v[22:23], s[100:101] op_sel_hi:[1,0]
	v_pk_mul_f32 v[154:155], v[24:25], s[100:101] op_sel_hi:[1,0]
	v_exp_f32_e32 v148, v148
	v_exp_f32_e32 v149, v149
	v_exp_f32_e32 v150, v150
	v_exp_f32_e32 v151, v151
	v_exp_f32_e32 v152, v152
	v_exp_f32_e32 v153, v153
	v_exp_f32_e32 v154, v154
	v_exp_f32_e32 v155, v155
	v_pk_mul_f32 v[30:31], v[30:31], v[26:27]
	v_pk_mul_f32 v[32:33], v[32:33], v[28:29]
	v_pk_mul_f32 v[22:23], v[22:23], v[18:19]
	v_pk_mul_f32 v[24:25], v[24:25], v[20:21]
	v_pk_add_f32 v[148:149], v[148:149], 1.0 op_sel_hi:[1,0]
	v_pk_add_f32 v[150:151], v[150:151], 1.0 op_sel_hi:[1,0]
	v_pk_add_f32 v[152:153], v[152:153], 1.0 op_sel_hi:[1,0]
	v_pk_add_f32 v[154:155], v[154:155], 1.0 op_sel_hi:[1,0]
	v_rcp_f32_e32 v148, v148
	v_rcp_f32_e32 v149, v149
	v_rcp_f32_e32 v150, v150
	v_rcp_f32_e32 v151, v151
	v_rcp_f32_e32 v152, v152
	v_rcp_f32_e32 v153, v153
	v_rcp_f32_e32 v154, v154
	v_rcp_f32_e32 v155, v155
	s_nop 0
	v_pk_mul_f32 v[30:31], v[148:149], v[30:31]
	v_pk_mul_f32 v[32:33], v[150:151], v[32:33]
	v_pk_mul_f32 v[22:23], v[152:153], v[22:23]
	v_pk_mul_f32 v[24:25], v[154:155], v[24:25]
	v_cvt_pk_bf16_f32 v26, v30, v31
	v_cvt_pk_bf16_f32 v27, v32, v33
	v_cvt_pk_bf16_f32 v28, v22, v23
	v_cvt_pk_bf16_f32 v29, v24, v25
	global_store_dwordx4 v[172:173], v[26:29], off sc1
	v_lshl_add_u64 v[172:173], v[172:173], 0, s[98:99]
	v_pk_mul_f32 v[156:157], v[14:15], s[100:101] op_sel_hi:[1,0]
	v_pk_mul_f32 v[158:159], v[16:17], s[100:101] op_sel_hi:[1,0]
	v_pk_mul_f32 v[160:161], v[6:7], s[100:101] op_sel_hi:[1,0]
	v_pk_mul_f32 v[162:163], v[8:9], s[100:101] op_sel_hi:[1,0]
	v_exp_f32_e32 v156, v156
	v_exp_f32_e32 v157, v157
	v_exp_f32_e32 v158, v158
	v_exp_f32_e32 v159, v159
	v_exp_f32_e32 v160, v160
	v_exp_f32_e32 v161, v161
	v_exp_f32_e32 v162, v162
	v_exp_f32_e32 v163, v163
	v_pk_mul_f32 v[14:15], v[14:15], v[10:11]
	v_pk_mul_f32 v[16:17], v[16:17], v[12:13]
	v_pk_mul_f32 v[6:7], v[6:7], v[2:3]
	v_pk_mul_f32 v[8:9], v[8:9], v[4:5]
	v_pk_add_f32 v[156:157], v[156:157], 1.0 op_sel_hi:[1,0]
	v_pk_add_f32 v[158:159], v[158:159], 1.0 op_sel_hi:[1,0]
	v_pk_add_f32 v[160:161], v[160:161], 1.0 op_sel_hi:[1,0]
	v_pk_add_f32 v[162:163], v[162:163], 1.0 op_sel_hi:[1,0]
	v_rcp_f32_e32 v156, v156
	v_rcp_f32_e32 v157, v157
	v_rcp_f32_e32 v158, v158
	v_rcp_f32_e32 v159, v159
	v_rcp_f32_e32 v160, v160
	v_rcp_f32_e32 v161, v161
	v_rcp_f32_e32 v162, v162
	v_rcp_f32_e32 v163, v163
	s_nop 0
	v_pk_mul_f32 v[14:15], v[156:157], v[14:15]
	v_pk_mul_f32 v[16:17], v[158:159], v[16:17]
	v_pk_mul_f32 v[6:7], v[160:161], v[6:7]
	v_pk_mul_f32 v[8:9], v[162:163], v[8:9]
	v_cvt_pk_bf16_f32 v10, v14, v15
	v_cvt_pk_bf16_f32 v11, v16, v17
	v_cvt_pk_bf16_f32 v12, v6, v7
	v_cvt_pk_bf16_f32 v13, v8, v9
	global_store_dwordx4 v[172:173], v[10:13], off sc1
.Lt9_eend:
	s_andn2_b64 vcc, exec, s[0:1]
	s_mov_b64 s[0:1], -1
	s_cbranch_vccnz .LBB0_973
	s_andn2_b64 vcc, exec, s[6:7]
	s_cbranch_vccnz .LBB0_972
	s_barrier
	s_branch .LBB0_972

.Ld1c_begin:
	s_mov_b64 s[98:99], s[4:5]
	s_sub_u32 s100, s94, 0xb8
	s_subb_u32 s101, s95, 0
	s_load_dwordx4 s[44:47], s[100:101], 0x60
	s_load_dwordx2 s[48:49], s[100:101], 0x70
	s_load_dwordx2 s[58:59], s[100:101], 0x18
	s_load_dwordx2 s[60:61], s[100:101], 0x20
	s_waitcnt lgkmcnt(0)
	s_cmpk_gt_i32 s3, 0xe0
	s_cselect_b32 s12, 0xe0, 0
	s_cmp_lt_i32 s2, s12
	s_cbranch_scc1 .Ld1c_end
	s_sub_i32 s0, s2, s12
	s_lshl_b32 s13, s0, 3
	s_add_i32 s13, s13, s33
	s_sub_i32 s14, s3, s12
	s_cmpk_gt_u32 s13, 0x197f
	s_cbranch_scc1 .Ld1c_end
	v_lshlrev_b32_e32 v2, 3, v0
	s_lshl_b32 s4, s33, 14
	v_lshrrev_b32_e32 v19, 3, v164
	v_and_b32_e32 v26, 56, v2
	s_add_i32 s0, s4, 0
	v_mul_u32_u24_e32 v2, 0x84, v26
	v_lshlrev_b32_e32 v13, 2, v19
	v_mov_b32_e32 v3, 0
	v_add3_u32 v44, s0, v2, v13
	v_lshlrev_b32_e32 v2, 1, v26
	v_lshl_add_u64 v[10:11], s[28:29], 0, v[2:3]
	s_mov_b64 s[0:1], 0x2900000
	v_lshl_add_u64 v[4:5], v[10:11], 0, s[0:1]
	s_mov_b64 s[0:1], 0x2300000
	s_lshl_b32 s15, s14, 3
	v_lshl_add_u64 v[6:7], v[10:11], 0, s[0:1]
	s_mov_b64 s[0:1], 0x1d80000
	s_add_u32 s18, s28, 0x2e00000
	v_lshl_add_u64 v[8:9], v[10:11], 0, s[0:1]
	s_mov_b64 s[0:1], 0x1280000
	s_addc_u32 s19, s29, 0
	v_lshl_add_u64 v[10:11], v[10:11], 0, s[0:1]
	s_lshl_b32 s0, s2, 3
	v_lshrrev_b32_e32 v1, 5, v164
	v_mov_b32_e32 v2, 0x6000
	s_add_i32 s0, s33, s0
	s_lshl_b32 s1, s12, 3
	v_and_b32_e32 v12, 31, v0
	v_lshl_or_b32 v49, v19, 13, v2
	v_mul_u32_u24_e32 v2, 0x84, v1
	s_sub_i32 s0, s0, s1
	v_and_b32_e32 v48, 16, v13
	v_or_b32_e32 v55, 0x80c, v13
	v_or_b32_e32 v56, 12, v13
	v_or_b32_e32 v13, s4, v2
	v_lshlrev_b32_e32 v2, 2, v12
	s_add_i32 s20, s0, 0xffffe780
	s_lshl_b32 s0, s3, 8
	s_lshl_b32 s1, s12, 8
	v_bfe_u32 v18, v0, 5, 1
	v_add3_u32 v57, v13, v2, 0
	v_lshl_add_u64 v[12:13], s[60:61], 0, v[2:3]
	s_sub_i32 s22, s0, s1
	s_lshl_b32 s0, s3, 5
	s_lshl_b32 s1, s12, 5
	v_readlane_b32 s60, v244, 0
	v_mul_u32_u24_e32 v20, 0x3000, v18
	s_sub_i32 s24, s0, s1
	v_readlane_b32 s61, v244, 1
	v_readlane_b32 s64, v244, 4
	v_readlane_b32 s65, v244, 5
	s_lshl_b32 s0, s13, 1
	s_lshl_b32 s1, s3, 4
	s_lshl_b32 s4, s12, 4
	v_mul_hi_u32_u24_e32 v21, 0x3000, v18
	v_or_b32_e32 v20, v20, v2
	s_mov_b32 s5, 0
	v_or_b32_e32 v45, 8, v19
	v_or_b32_e32 v46, 16, v19
	v_or_b32_e32 v47, 24, v19
	v_or_b32_e32 v50, 0x800, v48
	v_or_b32_e32 v51, 0x804, v48
	v_or_b32_e32 v52, 4, v48
	v_or_b32_e32 v53, 0x808, v48
	v_or_b32_e32 v54, 8, v48
	s_lshl_b32 s21, s13, 5
	v_or_b32_e32 v58, 14, v1
	s_lshl_b32 s23, s13, 2
	v_or_b32_e32 v59, 12, v1
	v_or_b32_e32 v60, 10, v1
	v_or_b32_e32 v61, 8, v1
	v_or_b32_e32 v62, 6, v1
	v_or_b32_e32 v63, 4, v1
	v_or_b32_e32 v64, 2, v1
	v_lshl_add_u64 v[14:15], s[64:65], 0, v[2:3]
	s_add_i32 s25, s0, 0x7fffd300
	s_sub_i32 s26, s1, s4
	v_lshl_add_u64 v[16:17], s[48:49], 0, v[2:3]
	v_lshl_add_u64 v[20:21], s[48:49], 0, v[20:21]
	v_lshl_add_u64 v[22:23], s[46:47], 0, v[2:3]
	s_add_i32 s27, s0, 0x7fffea00
	v_lshl_add_u64 v[24:25], s[44:45], 0, v[2:3]
	s_movk_i32 s44, 0xaff
	v_lshlrev_b32_e32 v26, 1, v26
	s_movk_i32 s45, 0x3e3
	s_movk_i32 s46, 0x2000
	s_movk_i32 s47, 0x4000
	s_mov_b32 s48, 0x1f1800
	s_movk_i32 s49, 0x7e3
	s_movk_i32 s56, 0x5000
	s_mov_b32 s57, 0xb000
	s_movk_i32 s60, 0x5800
	v_mov_b32_e32 v65, 0x3e3
	v_mov_b32_e32 v66, 0x5800
	v_mov_b32_e32 v67, 0xfffff500
	v_mov_b32_e32 v68, 0x80
	v_mov_b32_e32 v69, 0x63
	s_mov_b32 s61, s13
	v_readlane_b32 s62, v244, 2
	v_readlane_b32 s63, v244, 3
	v_readlane_b32 s66, v244, 6
	v_readlane_b32 s67, v244, 7
	s_branch .Ld1c_268

.Ld1c_268:
	s_cmpk_gt_i32 s61, 0xdbf
	s_mov_b64 s[0:1], -1
	s_cbranch_scc0 .Ld1c_267
	s_lshl_b32 s0, s21, 2
	s_and_b32 s10, s0, 0xf80
	s_cmpk_gt_u32 s61, 0x107f
	s_mov_b64 s[0:1], -1
	s_cbranch_scc0 .Ld1c_309
	s_branch .Ld1c_end
	s_cmpk_gt_u32 s61, 0x167f
	s_cbranch_scc0 .Ld1c_280
	s_cmpk_gt_u32 s61, 0x187f
	s_cbranch_scc0 .Ld1c_275
	s_lshr_b32 s8, s21, 5
	s_lshr_b32 s4, s20, 7
	s_lshl_b64 s[0:1], s[4:5], 20
	s_and_b32 s4, s8, 15
	s_lshl_b32 s4, s4, 7
	s_or_b32 s0, s0, s4
	s_and_b32 s4, s23, 0x1c0
	v_or_b32_e32 v2, s4, v58
	v_lshl_or_b32 v42, v2, 11, s0
	v_mov_b32_e32 v43, s1
	v_or_b32_e32 v2, s4, v59
	v_lshl_add_u64 v[28:29], v[12:13], 0, v[42:43]
	v_lshl_or_b32 v42, v2, 11, s0
	v_or_b32_e32 v2, s4, v60
	v_lshl_add_u64 v[30:31], v[12:13], 0, v[42:43]
	v_lshl_or_b32 v42, v2, 11, s0
	v_or_b32_e32 v2, s4, v61
	v_lshl_add_u64 v[32:33], v[12:13], 0, v[42:43]
	v_lshl_or_b32 v42, v2, 11, s0
	v_or_b32_e32 v2, s4, v62
	v_lshl_add_u64 v[34:35], v[12:13], 0, v[42:43]
	v_lshl_or_b32 v42, v2, 11, s0
	v_or_b32_e32 v2, s4, v63
	v_lshl_add_u64 v[36:37], v[12:13], 0, v[42:43]
	v_lshl_or_b32 v42, v2, 11, s0
	v_or_b32_e32 v2, s4, v64
	v_lshl_add_u64 v[38:39], v[12:13], 0, v[42:43]
	v_lshl_or_b32 v42, v2, 11, s0
	v_or_b32_e32 v2, s4, v1
	v_lshl_add_u64 v[40:41], v[12:13], 0, v[42:43]
	v_lshl_or_b32 v42, v2, 11, s0
	v_lshl_add_u64 v[42:43], v[12:13], 0, v[42:43]
	s_mov_b64 s[0:1], 0
	v_mov_b32_e32 v2, v57
